# hand-scheduled EpiGU epilogue for P5 and P11: pipelined part loads with counted waits, no v_mov shuffles
# baseline (speedup 1.0000x reference)
; __device__ __forceinline__ u32x4v pack8(const f32x4& a, const f32x4& b) { u32x4v w; w.x = cvt_pk_bf16(a[0], a[1]); w.y = cvt_pk_bf16(a[2], a[3]); w.z = cvt_pk_bf16(b[0], b[1]); w.w = cvt_pk_bf16(b[2], b[3]); return w; }
; __device__ __forceinline__ float rstd_from_partials(const float* part, int row) {
;     const f32x4* p = (const f32x4*)(part + (size_t)row * 16); const f32x4 a = p[0], b = p[1], c = p[2], d = p[3];
;     const float s = ((a[0] + a[1]) + (a[2] + a[3])) + ((b[0] + b[1]) + (b[2] + b[3])) + ((c[0] + c[1]) + (c[2] + c[3])) + ((d[0] + d[1]) + (d[2] + d[3]));
;     return __builtin_amdgcn_rsqf(s * (1.0f / 1024.0f) + 1e-6f);
;     __device__ __forceinline__ void operator()(const f32x4 (&acc)[2][2][4][2], const Unit& u, int wr, int wc, int fr, int fq) const {
;     ...
;             for (int m = 0; m < 4; ++m) { const int r = row0 + ai * HALF + m * 16; const float rs = rstd_from_partials(part, r);
;                 f32x4 o[2];
; #pragma unroll
;                 for (int n = 0; n < 2; ++n) { const f32x4 g = acc[ai][0][m][n] * rs, up = acc[ai][1][m][n] * rs;
; #pragma unroll
;                     for (int e = 0; e < 4; ++e) o[n][e] = g[e] * __builtin_amdgcn_rcpf(1.0f + __builtin_amdgcn_exp2f(-1.44269504089f * g[e])) * up[e]; }
;                 *(u32x4v*)(H + (size_t)r * 2816 + hc0) = pack8(o[0], o[1]); }
.LBB0_578:
	v_lshl_add_u32 v144, s28, 8, v146
	v_lshlrev_b32_e32 v145, 6, v144
	v_add_u32_e32 v153, 0x2000, v145
	global_load_dwordx4 v[154:157], v145, s[70:71] offset:0
	global_load_dwordx4 v[158:161], v145, s[70:71] offset:16
	global_load_dwordx4 v[162:165], v145, s[70:71] offset:32
	global_load_dwordx4 v[166:169], v145, s[70:71] offset:48
	global_load_dwordx4 v[170:173], v145, s[70:71] offset:1024
	global_load_dwordx4 v[174:177], v145, s[70:71] offset:1040
	global_load_dwordx4 v[178:181], v145, s[70:71] offset:1056
	global_load_dwordx4 v[182:185], v145, s[70:71] offset:1072
	global_load_dwordx4 v[186:189], v145, s[70:71] offset:2048
	global_load_dwordx4 v[190:193], v145, s[70:71] offset:2064
	global_load_dwordx4 v[194:197], v145, s[70:71] offset:2080
	global_load_dwordx4 v[198:201], v145, s[70:71] offset:2096
	global_load_dwordx4 v[202:205], v145, s[70:71] offset:3072
	global_load_dwordx4 v[206:209], v145, s[70:71] offset:3088
	global_load_dwordx4 v[210:213], v145, s[70:71] offset:3104
	global_load_dwordx4 v[214:217], v145, s[70:71] offset:3120
	v_mul_u32_u24_e32 v218, s55, v144
	v_lshl_or_b32 v219, s56, 7, v148
	v_lshl_add_u32 v218, v219, 1, v218
	s_waitcnt vmcnt(12)
	v_add_f32_e32 v230, v154, v155
	v_add_f32_e32 v231, v156, v157
	v_add_f32_e32 v232, v158, v159
	v_add_f32_e32 v233, v160, v161
	v_add_f32_e32 v234, v162, v163
	v_add_f32_e32 v235, v164, v165
	v_add_f32_e32 v236, v166, v167
	v_add_f32_e32 v237, v168, v169
	v_add_f32_e32 v230, v230, v231
	v_add_f32_e32 v232, v232, v233
	v_add_f32_e32 v234, v234, v235
	v_add_f32_e32 v236, v236, v237
	v_add_f32_e32 v230, v230, v232
	v_add_f32_e32 v230, v230, v234
	v_add_f32_e32 v230, v230, v236
	v_fmamk_f32 v230, v230, 0x3a800000, v152
	v_rsq_f32_e32 v222, v230
	global_load_dwordx4 v[154:157], v153, s[70:71] offset:0
	global_load_dwordx4 v[158:161], v153, s[70:71] offset:16
	global_load_dwordx4 v[162:165], v153, s[70:71] offset:32
	global_load_dwordx4 v[166:169], v153, s[70:71] offset:48
	v_mov_b32_e32 v238, v218
	v_mul_f32_e32 v116, v116, v222
	v_mul_f32_e32 v117, v117, v222
	v_mul_f32_e32 v118, v118, v222
	v_mul_f32_e32 v119, v119, v222
	v_mul_f32_e32 v112, v112, v222
	v_mul_f32_e32 v113, v113, v222
	v_mul_f32_e32 v114, v114, v222
	v_mul_f32_e32 v115, v115, v222
	v_mul_f32_e32 v124, v124, v222
	v_mul_f32_e32 v125, v125, v222
	v_mul_f32_e32 v126, v126, v222
	v_mul_f32_e32 v127, v127, v222
	v_mul_f32_e32 v120, v120, v222
	v_mul_f32_e32 v121, v121, v222
	v_mul_f32_e32 v122, v122, v222
	v_mul_f32_e32 v123, v123, v222
	v_mul_f32_e32 v230, 0xbfb8aa3b, v116
	v_mul_f32_e32 v231, 0xbfb8aa3b, v117
	v_mul_f32_e32 v232, 0xbfb8aa3b, v118
	v_mul_f32_e32 v233, 0xbfb8aa3b, v119
	v_mul_f32_e32 v234, 0xbfb8aa3b, v112
	v_mul_f32_e32 v235, 0xbfb8aa3b, v113
	v_mul_f32_e32 v236, 0xbfb8aa3b, v114
	v_mul_f32_e32 v237, 0xbfb8aa3b, v115
	v_exp_f32_e32 v230, v230
	v_exp_f32_e32 v231, v231
	v_exp_f32_e32 v232, v232
	v_exp_f32_e32 v233, v233
	v_exp_f32_e32 v234, v234
	v_exp_f32_e32 v235, v235
	v_exp_f32_e32 v236, v236
	v_exp_f32_e32 v237, v237
	v_add_f32_e32 v230, 1.0, v230
	v_add_f32_e32 v231, 1.0, v231
	v_add_f32_e32 v232, 1.0, v232
	v_add_f32_e32 v233, 1.0, v233
	v_add_f32_e32 v234, 1.0, v234
	v_add_f32_e32 v235, 1.0, v235
	v_add_f32_e32 v236, 1.0, v236
	v_add_f32_e32 v237, 1.0, v237
	v_rcp_f32_e32 v230, v230
	v_rcp_f32_e32 v231, v231
	v_rcp_f32_e32 v232, v232
	v_rcp_f32_e32 v233, v233
	v_rcp_f32_e32 v234, v234
	v_rcp_f32_e32 v235, v235
	v_rcp_f32_e32 v236, v236
	v_rcp_f32_e32 v237, v237
	v_mul_f32_e32 v116, v116, v230
	v_mul_f32_e32 v117, v117, v231
	v_mul_f32_e32 v118, v118, v232
	v_mul_f32_e32 v119, v119, v233
	v_mul_f32_e32 v112, v112, v234
	v_mul_f32_e32 v113, v113, v235
	v_mul_f32_e32 v114, v114, v236
	v_mul_f32_e32 v115, v115, v237
	v_mul_f32_e32 v116, v124, v116
	v_mul_f32_e32 v117, v125, v117
	v_mul_f32_e32 v118, v126, v118
	v_mul_f32_e32 v119, v127, v119
	v_mul_f32_e32 v112, v120, v112
	v_mul_f32_e32 v113, v121, v113
	v_mul_f32_e32 v114, v122, v114
	v_mul_f32_e32 v115, v123, v115
	v_cvt_pk_bf16_f32 v124, v116, v117
	v_cvt_pk_bf16_f32 v125, v118, v119
	v_cvt_pk_bf16_f32 v126, v112, v113
	v_cvt_pk_bf16_f32 v127, v114, v115
	global_store_dwordx4 v238, v[124:127], s[40:41]
	s_waitcnt vmcnt(12)
	v_add_f32_e32 v230, v170, v171
	v_add_f32_e32 v231, v172, v173
	v_add_f32_e32 v232, v174, v175
	v_add_f32_e32 v233, v176, v177
	v_add_f32_e32 v234, v178, v179
	v_add_f32_e32 v235, v180, v181
	v_add_f32_e32 v236, v182, v183
	v_add_f32_e32 v237, v184, v185
	v_add_f32_e32 v230, v230, v231
	v_add_f32_e32 v232, v232, v233
	v_add_f32_e32 v234, v234, v235
	v_add_f32_e32 v236, v236, v237
	v_add_f32_e32 v230, v230, v232
	v_add_f32_e32 v230, v230, v234
	v_add_f32_e32 v230, v230, v236
	v_fmamk_f32 v230, v230, 0x3a800000, v152
	v_rsq_f32_e32 v223, v230
	global_load_dwordx4 v[170:173], v153, s[70:71] offset:1024
	global_load_dwordx4 v[174:177], v153, s[70:71] offset:1040
	global_load_dwordx4 v[178:181], v153, s[70:71] offset:1056
	global_load_dwordx4 v[182:185], v153, s[70:71] offset:1072
	v_add_u32_e32 v239, 0x16000, v218
	v_mul_f32_e32 v100, v100, v223
	v_mul_f32_e32 v101, v101, v223
	v_mul_f32_e32 v102, v102, v223
	v_mul_f32_e32 v103, v103, v223
	v_mul_f32_e32 v96, v96, v223
	v_mul_f32_e32 v97, v97, v223
	v_mul_f32_e32 v98, v98, v223
	v_mul_f32_e32 v99, v99, v223
	v_mul_f32_e32 v108, v108, v223
	v_mul_f32_e32 v109, v109, v223
	v_mul_f32_e32 v110, v110, v223
	v_mul_f32_e32 v111, v111, v223
	v_mul_f32_e32 v104, v104, v223
	v_mul_f32_e32 v105, v105, v223
	v_mul_f32_e32 v106, v106, v223
	v_mul_f32_e32 v107, v107, v223
	v_mul_f32_e32 v230, 0xbfb8aa3b, v100
	v_mul_f32_e32 v231, 0xbfb8aa3b, v101
	v_mul_f32_e32 v232, 0xbfb8aa3b, v102
; __device__ __forceinline__ u32x4v pack8(const f32x4& a, const f32x4& b) { u32x4v w; w.x = cvt_pk_bf16(a[0], a[1]); w.y = cvt_pk_bf16(a[2], a[3]); w.z = cvt_pk_bf16(b[0], b[1]); w.w = cvt_pk_bf16(b[2], b[3]); return w; }
;     __device__ __forceinline__ void operator()(const f32x4 (&acc)[2][2][4][2], const Unit& u, int wr, int wc, int fr, int fq) const {
;     ...
;             for (int m = 0; m < 4; ++m) { const int r = row0 + ai * HALF + m * 16; const float rs = rstd_from_partials(part, r);
;                 f32x4 o[2];
; #pragma unroll
;                 for (int n = 0; n < 2; ++n) { const f32x4 g = acc[ai][0][m][n] * rs, up = acc[ai][1][m][n] * rs;
; #pragma unroll
;                     for (int e = 0; e < 4; ++e) o[n][e] = g[e] * __builtin_amdgcn_rcpf(1.0f + __builtin_amdgcn_exp2f(-1.44269504089f * g[e])) * up[e]; }
;                 *(u32x4v*)(H + (size_t)r * 2816 + hc0) = pack8(o[0], o[1]); }
	v_mul_f32_e32 v233, 0xbfb8aa3b, v103
	v_mul_f32_e32 v234, 0xbfb8aa3b, v96
	v_mul_f32_e32 v235, 0xbfb8aa3b, v97
	v_mul_f32_e32 v236, 0xbfb8aa3b, v98
	v_mul_f32_e32 v237, 0xbfb8aa3b, v99
	v_exp_f32_e32 v230, v230
	v_exp_f32_e32 v231, v231
	v_exp_f32_e32 v232, v232
	v_exp_f32_e32 v233, v233
	v_exp_f32_e32 v234, v234
	v_exp_f32_e32 v235, v235
	v_exp_f32_e32 v236, v236
	v_exp_f32_e32 v237, v237
	v_add_f32_e32 v230, 1.0, v230
	v_add_f32_e32 v231, 1.0, v231
	v_add_f32_e32 v232, 1.0, v232
	v_add_f32_e32 v233, 1.0, v233
	v_add_f32_e32 v234, 1.0, v234
	v_add_f32_e32 v235, 1.0, v235
	v_add_f32_e32 v236, 1.0, v236
	v_add_f32_e32 v237, 1.0, v237
	v_rcp_f32_e32 v230, v230
	v_rcp_f32_e32 v231, v231
	v_rcp_f32_e32 v232, v232
	v_rcp_f32_e32 v233, v233
	v_rcp_f32_e32 v234, v234
	v_rcp_f32_e32 v235, v235
	v_rcp_f32_e32 v236, v236
	v_rcp_f32_e32 v237, v237
	v_mul_f32_e32 v100, v100, v230
	v_mul_f32_e32 v101, v101, v231
	v_mul_f32_e32 v102, v102, v232
	v_mul_f32_e32 v103, v103, v233
	v_mul_f32_e32 v96, v96, v234
	v_mul_f32_e32 v97, v97, v235
	v_mul_f32_e32 v98, v98, v236
	v_mul_f32_e32 v99, v99, v237
	v_mul_f32_e32 v100, v108, v100
	v_mul_f32_e32 v101, v109, v101
	v_mul_f32_e32 v102, v110, v102
	v_mul_f32_e32 v103, v111, v103
	v_mul_f32_e32 v96, v104, v96
	v_mul_f32_e32 v97, v105, v97
	v_mul_f32_e32 v98, v106, v98
	v_mul_f32_e32 v99, v107, v99
	v_cvt_pk_bf16_f32 v108, v100, v101
	v_cvt_pk_bf16_f32 v109, v102, v103
	v_cvt_pk_bf16_f32 v110, v96, v97
	v_cvt_pk_bf16_f32 v111, v98, v99
	global_store_dwordx4 v239, v[108:111], s[40:41]
	s_waitcnt vmcnt(12)
	v_add_f32_e32 v230, v186, v187
	v_add_f32_e32 v231, v188, v189
	v_add_f32_e32 v232, v190, v191
	v_add_f32_e32 v233, v192, v193
	v_add_f32_e32 v234, v194, v195
	v_add_f32_e32 v235, v196, v197
	v_add_f32_e32 v236, v198, v199
	v_add_f32_e32 v237, v200, v201
	v_add_f32_e32 v230, v230, v231
	v_add_f32_e32 v232, v232, v233
	v_add_f32_e32 v234, v234, v235
	v_add_f32_e32 v236, v236, v237
	v_add_f32_e32 v230, v230, v232
	v_add_f32_e32 v230, v230, v234
	v_add_f32_e32 v230, v230, v236
	v_fmamk_f32 v230, v230, 0x3a800000, v152
	v_rsq_f32_e32 v224, v230
	global_load_dwordx4 v[186:189], v153, s[70:71] offset:2048
	global_load_dwordx4 v[190:193], v153, s[70:71] offset:2064
	global_load_dwordx4 v[194:197], v153, s[70:71] offset:2080
	global_load_dwordx4 v[198:201], v153, s[70:71] offset:2096
	v_add_u32_e32 v238, 0x2c000, v218
	v_mul_f32_e32 v84, v84, v224
	v_mul_f32_e32 v85, v85, v224
	v_mul_f32_e32 v86, v86, v224
	v_mul_f32_e32 v87, v87, v224
	v_mul_f32_e32 v80, v80, v224
	v_mul_f32_e32 v81, v81, v224
	v_mul_f32_e32 v82, v82, v224
	v_mul_f32_e32 v83, v83, v224
	v_mul_f32_e32 v92, v92, v224
	v_mul_f32_e32 v93, v93, v224
	v_mul_f32_e32 v94, v94, v224
	v_mul_f32_e32 v95, v95, v224
	v_mul_f32_e32 v88, v88, v224
	v_mul_f32_e32 v89, v89, v224
	v_mul_f32_e32 v90, v90, v224
	v_mul_f32_e32 v91, v91, v224
	v_mul_f32_e32 v230, 0xbfb8aa3b, v84
	v_mul_f32_e32 v231, 0xbfb8aa3b, v85
	v_mul_f32_e32 v232, 0xbfb8aa3b, v86
	v_mul_f32_e32 v233, 0xbfb8aa3b, v87
	v_mul_f32_e32 v234, 0xbfb8aa3b, v80
	v_mul_f32_e32 v235, 0xbfb8aa3b, v81
	v_mul_f32_e32 v236, 0xbfb8aa3b, v82
	v_mul_f32_e32 v237, 0xbfb8aa3b, v83
	v_exp_f32_e32 v230, v230
	v_exp_f32_e32 v231, v231
	v_exp_f32_e32 v232, v232
	v_exp_f32_e32 v233, v233
	v_exp_f32_e32 v234, v234
	v_exp_f32_e32 v235, v235
	v_exp_f32_e32 v236, v236
	v_exp_f32_e32 v237, v237
	v_add_f32_e32 v230, 1.0, v230
	v_add_f32_e32 v231, 1.0, v231
	v_add_f32_e32 v232, 1.0, v232
	v_add_f32_e32 v233, 1.0, v233
	v_add_f32_e32 v234, 1.0, v234
	v_add_f32_e32 v235, 1.0, v235
	v_add_f32_e32 v236, 1.0, v236
	v_add_f32_e32 v237, 1.0, v237
	v_rcp_f32_e32 v230, v230
	v_rcp_f32_e32 v231, v231
	v_rcp_f32_e32 v232, v232
	v_rcp_f32_e32 v233, v233
	v_rcp_f32_e32 v234, v234
	v_rcp_f32_e32 v235, v235
	v_rcp_f32_e32 v236, v236
	v_rcp_f32_e32 v237, v237
	v_mul_f32_e32 v84, v84, v230
	v_mul_f32_e32 v85, v85, v231
	v_mul_f32_e32 v86, v86, v232
	v_mul_f32_e32 v87, v87, v233
	v_mul_f32_e32 v80, v80, v234
	v_mul_f32_e32 v81, v81, v235
	v_mul_f32_e32 v82, v82, v236
	v_mul_f32_e32 v83, v83, v237
	v_mul_f32_e32 v84, v92, v84
	v_mul_f32_e32 v85, v93, v85
	v_mul_f32_e32 v86, v94, v86
	v_mul_f32_e32 v87, v95, v87
	v_mul_f32_e32 v80, v88, v80
	v_mul_f32_e32 v81, v89, v81
	v_mul_f32_e32 v82, v90, v82
	v_mul_f32_e32 v83, v91, v83
	v_cvt_pk_bf16_f32 v92, v84, v85
	v_cvt_pk_bf16_f32 v93, v86, v87
	v_cvt_pk_bf16_f32 v94, v80, v81
	v_cvt_pk_bf16_f32 v95, v82, v83
	global_store_dwordx4 v238, v[92:95], s[40:41]
	s_waitcnt vmcnt(12)
; __device__ __forceinline__ u32x4v pack8(const f32x4& a, const f32x4& b) { u32x4v w; w.x = cvt_pk_bf16(a[0], a[1]); w.y = cvt_pk_bf16(a[2], a[3]); w.z = cvt_pk_bf16(b[0], b[1]); w.w = cvt_pk_bf16(b[2], b[3]); return w; }
; __device__ __forceinline__ float rstd_from_partials(const float* part, int row) {
;     const f32x4* p = (const f32x4*)(part + (size_t)row * 16); const f32x4 a = p[0], b = p[1], c = p[2], d = p[3];
;     const float s = ((a[0] + a[1]) + (a[2] + a[3])) + ((b[0] + b[1]) + (b[2] + b[3])) + ((c[0] + c[1]) + (c[2] + c[3])) + ((d[0] + d[1]) + (d[2] + d[3]));
;     return __builtin_amdgcn_rsqf(s * (1.0f / 1024.0f) + 1e-6f);
;     __device__ __forceinline__ void operator()(const f32x4 (&acc)[2][2][4][2], const Unit& u, int wr, int wc, int fr, int fq) const {
;     ...
;             for (int m = 0; m < 4; ++m) { const int r = row0 + ai * HALF + m * 16; const float rs = rstd_from_partials(part, r);
;                 f32x4 o[2];
; #pragma unroll
;                 for (int n = 0; n < 2; ++n) { const f32x4 g = acc[ai][0][m][n] * rs, up = acc[ai][1][m][n] * rs;
; #pragma unroll
;                     for (int e = 0; e < 4; ++e) o[n][e] = g[e] * __builtin_amdgcn_rcpf(1.0f + __builtin_amdgcn_exp2f(-1.44269504089f * g[e])) * up[e]; }
;                 *(u32x4v*)(H + (size_t)r * 2816 + hc0) = pack8(o[0], o[1]); }
	v_add_f32_e32 v230, v202, v203
	v_add_f32_e32 v231, v204, v205
	v_add_f32_e32 v232, v206, v207
	v_add_f32_e32 v233, v208, v209
	v_add_f32_e32 v234, v210, v211
	v_add_f32_e32 v235, v212, v213
	v_add_f32_e32 v236, v214, v215
	v_add_f32_e32 v237, v216, v217
	v_add_f32_e32 v230, v230, v231
	v_add_f32_e32 v232, v232, v233
	v_add_f32_e32 v234, v234, v235
	v_add_f32_e32 v236, v236, v237
	v_add_f32_e32 v230, v230, v232
	v_add_f32_e32 v230, v230, v234
	v_add_f32_e32 v230, v230, v236
	v_fmamk_f32 v230, v230, 0x3a800000, v152
	v_rsq_f32_e32 v225, v230
	global_load_dwordx4 v[202:205], v153, s[70:71] offset:3072
	global_load_dwordx4 v[206:209], v153, s[70:71] offset:3088
	global_load_dwordx4 v[210:213], v153, s[70:71] offset:3104
	global_load_dwordx4 v[214:217], v153, s[70:71] offset:3120
	v_add_u32_e32 v239, 0x42000, v218
	v_mul_f32_e32 v68, v68, v225
	v_mul_f32_e32 v69, v69, v225
	v_mul_f32_e32 v70, v70, v225
	v_mul_f32_e32 v71, v71, v225
	v_mul_f32_e32 v64, v64, v225
	v_mul_f32_e32 v65, v65, v225
	v_mul_f32_e32 v66, v66, v225
	v_mul_f32_e32 v67, v67, v225
	v_mul_f32_e32 v76, v76, v225
	v_mul_f32_e32 v77, v77, v225
	v_mul_f32_e32 v78, v78, v225
	v_mul_f32_e32 v79, v79, v225
	v_mul_f32_e32 v72, v72, v225
	v_mul_f32_e32 v73, v73, v225
	v_mul_f32_e32 v74, v74, v225
	v_mul_f32_e32 v75, v75, v225
	v_mul_f32_e32 v230, 0xbfb8aa3b, v68
	v_mul_f32_e32 v231, 0xbfb8aa3b, v69
	v_mul_f32_e32 v232, 0xbfb8aa3b, v70
	v_mul_f32_e32 v233, 0xbfb8aa3b, v71
	v_mul_f32_e32 v234, 0xbfb8aa3b, v64
	v_mul_f32_e32 v235, 0xbfb8aa3b, v65
	v_mul_f32_e32 v236, 0xbfb8aa3b, v66
	v_mul_f32_e32 v237, 0xbfb8aa3b, v67
	v_exp_f32_e32 v230, v230
	v_exp_f32_e32 v231, v231
	v_exp_f32_e32 v232, v232
	v_exp_f32_e32 v233, v233
	v_exp_f32_e32 v234, v234
	v_exp_f32_e32 v235, v235
	v_exp_f32_e32 v236, v236
	v_exp_f32_e32 v237, v237
	v_add_f32_e32 v230, 1.0, v230
	v_add_f32_e32 v231, 1.0, v231
	v_add_f32_e32 v232, 1.0, v232
	v_add_f32_e32 v233, 1.0, v233
	v_add_f32_e32 v234, 1.0, v234
	v_add_f32_e32 v235, 1.0, v235
	v_add_f32_e32 v236, 1.0, v236
	v_add_f32_e32 v237, 1.0, v237
	v_rcp_f32_e32 v230, v230
	v_rcp_f32_e32 v231, v231
	v_rcp_f32_e32 v232, v232
	v_rcp_f32_e32 v233, v233
	v_rcp_f32_e32 v234, v234
	v_rcp_f32_e32 v235, v235
	v_rcp_f32_e32 v236, v236
	v_rcp_f32_e32 v237, v237
	v_mul_f32_e32 v68, v68, v230
	v_mul_f32_e32 v69, v69, v231
	v_mul_f32_e32 v70, v70, v232
	v_mul_f32_e32 v71, v71, v233
	v_mul_f32_e32 v64, v64, v234
	v_mul_f32_e32 v65, v65, v235
	v_mul_f32_e32 v66, v66, v236
	v_mul_f32_e32 v67, v67, v237
	v_mul_f32_e32 v68, v76, v68
	v_mul_f32_e32 v69, v77, v69
	v_mul_f32_e32 v70, v78, v70
	v_mul_f32_e32 v71, v79, v71
	v_mul_f32_e32 v64, v72, v64
	v_mul_f32_e32 v65, v73, v65
	v_mul_f32_e32 v66, v74, v66
	v_mul_f32_e32 v67, v75, v67
	v_cvt_pk_bf16_f32 v76, v68, v69
	v_cvt_pk_bf16_f32 v77, v70, v71
	v_cvt_pk_bf16_f32 v78, v64, v65
	v_cvt_pk_bf16_f32 v79, v66, v67
	global_store_dwordx4 v239, v[76:79], s[40:41]
	s_waitcnt vmcnt(12)
	v_add_f32_e32 v230, v154, v155
	v_add_f32_e32 v231, v156, v157
	v_add_f32_e32 v232, v158, v159
	v_add_f32_e32 v233, v160, v161
	v_add_f32_e32 v234, v162, v163
	v_add_f32_e32 v235, v164, v165
	v_add_f32_e32 v236, v166, v167
	v_add_f32_e32 v237, v168, v169
	v_add_f32_e32 v230, v230, v231
	v_add_f32_e32 v232, v232, v233
	v_add_f32_e32 v234, v234, v235
	v_add_f32_e32 v236, v236, v237
	v_add_f32_e32 v230, v230, v232
	v_add_f32_e32 v230, v230, v234
	v_add_f32_e32 v230, v230, v236
	v_fmamk_f32 v230, v230, 0x3a800000, v152
	v_rsq_f32_e32 v226, v230
	v_add_u32_e32 v238, 0xb0000, v218
	v_mul_f32_e32 v52, v52, v226
	v_mul_f32_e32 v53, v53, v226
	v_mul_f32_e32 v54, v54, v226
	v_mul_f32_e32 v55, v55, v226
	v_mul_f32_e32 v48, v48, v226
	v_mul_f32_e32 v49, v49, v226
	v_mul_f32_e32 v50, v50, v226
	v_mul_f32_e32 v51, v51, v226
	v_mul_f32_e32 v60, v60, v226
	v_mul_f32_e32 v61, v61, v226
	v_mul_f32_e32 v62, v62, v226
	v_mul_f32_e32 v63, v63, v226
	v_mul_f32_e32 v56, v56, v226
	v_mul_f32_e32 v57, v57, v226
	v_mul_f32_e32 v58, v58, v226
	v_mul_f32_e32 v59, v59, v226
	v_mul_f32_e32 v230, 0xbfb8aa3b, v52
	v_mul_f32_e32 v231, 0xbfb8aa3b, v53
	v_mul_f32_e32 v232, 0xbfb8aa3b, v54
	v_mul_f32_e32 v233, 0xbfb8aa3b, v55
	v_mul_f32_e32 v234, 0xbfb8aa3b, v48
	v_mul_f32_e32 v235, 0xbfb8aa3b, v49
	v_mul_f32_e32 v236, 0xbfb8aa3b, v50
	v_mul_f32_e32 v237, 0xbfb8aa3b, v51
	v_exp_f32_e32 v230, v230
	v_exp_f32_e32 v231, v231
	v_exp_f32_e32 v232, v232
	v_exp_f32_e32 v233, v233
	v_exp_f32_e32 v234, v234
	v_exp_f32_e32 v235, v235
	v_exp_f32_e32 v236, v236
	v_exp_f32_e32 v237, v237
	v_add_f32_e32 v230, 1.0, v230
	v_add_f32_e32 v231, 1.0, v231
	v_add_f32_e32 v232, 1.0, v232
	v_add_f32_e32 v233, 1.0, v233
	v_add_f32_e32 v234, 1.0, v234
	v_add_f32_e32 v235, 1.0, v235
	v_add_f32_e32 v236, 1.0, v236
	v_add_f32_e32 v237, 1.0, v237
	v_rcp_f32_e32 v230, v230
	v_rcp_f32_e32 v231, v231
	v_rcp_f32_e32 v232, v232
	v_rcp_f32_e32 v233, v233
	v_rcp_f32_e32 v234, v234
	v_rcp_f32_e32 v235, v235
	v_rcp_f32_e32 v236, v236
	v_rcp_f32_e32 v237, v237
	v_mul_f32_e32 v52, v52, v230
	v_mul_f32_e32 v53, v53, v231
	v_mul_f32_e32 v54, v54, v232
	v_mul_f32_e32 v55, v55, v233
	v_mul_f32_e32 v48, v48, v234
	v_mul_f32_e32 v49, v49, v235
	v_mul_f32_e32 v50, v50, v236
	v_mul_f32_e32 v51, v51, v237
	v_mul_f32_e32 v52, v60, v52
	v_mul_f32_e32 v53, v61, v53
	v_mul_f32_e32 v54, v62, v54
	v_mul_f32_e32 v55, v63, v55
	v_mul_f32_e32 v48, v56, v48
	v_mul_f32_e32 v49, v57, v49
	v_mul_f32_e32 v50, v58, v50
	v_mul_f32_e32 v51, v59, v51
	v_cvt_pk_bf16_f32 v60, v52, v53
	v_cvt_pk_bf16_f32 v61, v54, v55
	v_cvt_pk_bf16_f32 v62, v48, v49
	v_cvt_pk_bf16_f32 v63, v50, v51
	global_store_dwordx4 v238, v[60:63], s[40:41]
	s_waitcnt vmcnt(8)
; __device__ __forceinline__ u32x4v pack8(const f32x4& a, const f32x4& b) { u32x4v w; w.x = cvt_pk_bf16(a[0], a[1]); w.y = cvt_pk_bf16(a[2], a[3]); w.z = cvt_pk_bf16(b[0], b[1]); w.w = cvt_pk_bf16(b[2], b[3]); return w; }
; __device__ __forceinline__ float rstd_from_partials(const float* part, int row) {
;     const f32x4* p = (const f32x4*)(part + (size_t)row * 16); const f32x4 a = p[0], b = p[1], c = p[2], d = p[3];
;     const float s = ((a[0] + a[1]) + (a[2] + a[3])) + ((b[0] + b[1]) + (b[2] + b[3])) + ((c[0] + c[1]) + (c[2] + c[3])) + ((d[0] + d[1]) + (d[2] + d[3]));
;     return __builtin_amdgcn_rsqf(s * (1.0f / 1024.0f) + 1e-6f);
;     __device__ __forceinline__ void operator()(const f32x4 (&acc)[2][2][4][2], const Unit& u, int wr, int wc, int fr, int fq) const {
;     ...
;             for (int m = 0; m < 4; ++m) { const int r = row0 + ai * HALF + m * 16; const float rs = rstd_from_partials(part, r);
;                 f32x4 o[2];
; #pragma unroll
;                 for (int n = 0; n < 2; ++n) { const f32x4 g = acc[ai][0][m][n] * rs, up = acc[ai][1][m][n] * rs;
; #pragma unroll
;                     for (int e = 0; e < 4; ++e) o[n][e] = g[e] * __builtin_amdgcn_rcpf(1.0f + __builtin_amdgcn_exp2f(-1.44269504089f * g[e])) * up[e]; }
;                 *(u32x4v*)(H + (size_t)r * 2816 + hc0) = pack8(o[0], o[1]); }
	v_add_f32_e32 v230, v170, v171
	v_add_f32_e32 v231, v172, v173
	v_add_f32_e32 v232, v174, v175
	v_add_f32_e32 v233, v176, v177
	v_add_f32_e32 v234, v178, v179
	v_add_f32_e32 v235, v180, v181
	v_add_f32_e32 v236, v182, v183
	v_add_f32_e32 v237, v184, v185
	v_add_f32_e32 v230, v230, v231
	v_add_f32_e32 v232, v232, v233
	v_add_f32_e32 v234, v234, v235
	v_add_f32_e32 v236, v236, v237
	v_add_f32_e32 v230, v230, v232
	v_add_f32_e32 v230, v230, v234
	v_add_f32_e32 v230, v230, v236
	v_fmamk_f32 v230, v230, 0x3a800000, v152
	v_rsq_f32_e32 v227, v230
	v_add_u32_e32 v239, 0xc6000, v218
	v_mul_f32_e32 v36, v36, v227
	v_mul_f32_e32 v37, v37, v227
	v_mul_f32_e32 v38, v38, v227
	v_mul_f32_e32 v39, v39, v227
	v_mul_f32_e32 v32, v32, v227
	v_mul_f32_e32 v33, v33, v227
	v_mul_f32_e32 v34, v34, v227
	v_mul_f32_e32 v35, v35, v227
	v_mul_f32_e32 v44, v44, v227
	v_mul_f32_e32 v45, v45, v227
	v_mul_f32_e32 v46, v46, v227
	v_mul_f32_e32 v47, v47, v227
	v_mul_f32_e32 v40, v40, v227
	v_mul_f32_e32 v41, v41, v227
	v_mul_f32_e32 v42, v42, v227
	v_mul_f32_e32 v43, v43, v227
	v_mul_f32_e32 v230, 0xbfb8aa3b, v36
	v_mul_f32_e32 v231, 0xbfb8aa3b, v37
	v_mul_f32_e32 v232, 0xbfb8aa3b, v38
	v_mul_f32_e32 v233, 0xbfb8aa3b, v39
	v_mul_f32_e32 v234, 0xbfb8aa3b, v32
	v_mul_f32_e32 v235, 0xbfb8aa3b, v33
	v_mul_f32_e32 v236, 0xbfb8aa3b, v34
	v_mul_f32_e32 v237, 0xbfb8aa3b, v35
	v_exp_f32_e32 v230, v230
	v_exp_f32_e32 v231, v231
	v_exp_f32_e32 v232, v232
	v_exp_f32_e32 v233, v233
	v_exp_f32_e32 v234, v234
	v_exp_f32_e32 v235, v235
	v_exp_f32_e32 v236, v236
	v_exp_f32_e32 v237, v237
	v_add_f32_e32 v230, 1.0, v230
	v_add_f32_e32 v231, 1.0, v231
	v_add_f32_e32 v232, 1.0, v232
	v_add_f32_e32 v233, 1.0, v233
	v_add_f32_e32 v234, 1.0, v234
	v_add_f32_e32 v235, 1.0, v235
	v_add_f32_e32 v236, 1.0, v236
	v_add_f32_e32 v237, 1.0, v237
	v_rcp_f32_e32 v230, v230
	v_rcp_f32_e32 v231, v231
	v_rcp_f32_e32 v232, v232
	v_rcp_f32_e32 v233, v233
	v_rcp_f32_e32 v234, v234
	v_rcp_f32_e32 v235, v235
	v_rcp_f32_e32 v236, v236
	v_rcp_f32_e32 v237, v237
	v_mul_f32_e32 v36, v36, v230
	v_mul_f32_e32 v37, v37, v231
	v_mul_f32_e32 v38, v38, v232
	v_mul_f32_e32 v39, v39, v233
	v_mul_f32_e32 v32, v32, v234
	v_mul_f32_e32 v33, v33, v235
	v_mul_f32_e32 v34, v34, v236
	v_mul_f32_e32 v35, v35, v237
	v_mul_f32_e32 v36, v44, v36
	v_mul_f32_e32 v37, v45, v37
	v_mul_f32_e32 v38, v46, v38
	v_mul_f32_e32 v39, v47, v39
	v_mul_f32_e32 v32, v40, v32
	v_mul_f32_e32 v33, v41, v33
	v_mul_f32_e32 v34, v42, v34
	v_mul_f32_e32 v35, v43, v35
	v_cvt_pk_bf16_f32 v44, v36, v37
	v_cvt_pk_bf16_f32 v45, v38, v39
	v_cvt_pk_bf16_f32 v46, v32, v33
	v_cvt_pk_bf16_f32 v47, v34, v35
	global_store_dwordx4 v239, v[44:47], s[40:41]
	s_waitcnt vmcnt(4)
	v_add_f32_e32 v230, v186, v187
	v_add_f32_e32 v231, v188, v189
	v_add_f32_e32 v232, v190, v191
	v_add_f32_e32 v233, v192, v193
	v_add_f32_e32 v234, v194, v195
	v_add_f32_e32 v235, v196, v197
	v_add_f32_e32 v236, v198, v199
	v_add_f32_e32 v237, v200, v201
	v_add_f32_e32 v230, v230, v231
	v_add_f32_e32 v232, v232, v233
	v_add_f32_e32 v234, v234, v235
	v_add_f32_e32 v236, v236, v237
	v_add_f32_e32 v230, v230, v232
	v_add_f32_e32 v230, v230, v234
	v_add_f32_e32 v230, v230, v236
	v_fmamk_f32 v230, v230, 0x3a800000, v152
	v_rsq_f32_e32 v228, v230
	v_add_u32_e32 v238, 0xdc000, v218
	v_mul_f32_e32 v20, v20, v228
	v_mul_f32_e32 v21, v21, v228
	v_mul_f32_e32 v22, v22, v228
	v_mul_f32_e32 v23, v23, v228
	v_mul_f32_e32 v16, v16, v228
	v_mul_f32_e32 v17, v17, v228
	v_mul_f32_e32 v18, v18, v228
	v_mul_f32_e32 v19, v19, v228
	v_mul_f32_e32 v28, v28, v228
	v_mul_f32_e32 v29, v29, v228
	v_mul_f32_e32 v30, v30, v228
	v_mul_f32_e32 v31, v31, v228
	v_mul_f32_e32 v24, v24, v228
	v_mul_f32_e32 v25, v25, v228
	v_mul_f32_e32 v26, v26, v228
	v_mul_f32_e32 v27, v27, v228
	v_mul_f32_e32 v230, 0xbfb8aa3b, v20
	v_mul_f32_e32 v231, 0xbfb8aa3b, v21
	v_mul_f32_e32 v232, 0xbfb8aa3b, v22
	v_mul_f32_e32 v233, 0xbfb8aa3b, v23
	v_mul_f32_e32 v234, 0xbfb8aa3b, v16
	v_mul_f32_e32 v235, 0xbfb8aa3b, v17
	v_mul_f32_e32 v236, 0xbfb8aa3b, v18
	v_mul_f32_e32 v237, 0xbfb8aa3b, v19
	v_exp_f32_e32 v230, v230
	v_exp_f32_e32 v231, v231
	v_exp_f32_e32 v232, v232
	v_exp_f32_e32 v233, v233
	v_exp_f32_e32 v234, v234
	v_exp_f32_e32 v235, v235
	v_exp_f32_e32 v236, v236
	v_exp_f32_e32 v237, v237
	v_add_f32_e32 v230, 1.0, v230
	v_add_f32_e32 v231, 1.0, v231
	v_add_f32_e32 v232, 1.0, v232
	v_add_f32_e32 v233, 1.0, v233
	v_add_f32_e32 v234, 1.0, v234
	v_add_f32_e32 v235, 1.0, v235
	v_add_f32_e32 v236, 1.0, v236
	v_add_f32_e32 v237, 1.0, v237
	v_rcp_f32_e32 v230, v230
	v_rcp_f32_e32 v231, v231
	v_rcp_f32_e32 v232, v232
	v_rcp_f32_e32 v233, v233
	v_rcp_f32_e32 v234, v234
	v_rcp_f32_e32 v235, v235
	v_rcp_f32_e32 v236, v236
	v_rcp_f32_e32 v237, v237
	v_mul_f32_e32 v20, v20, v230
	v_mul_f32_e32 v21, v21, v231
	v_mul_f32_e32 v22, v22, v232
	v_mul_f32_e32 v23, v23, v233
	v_mul_f32_e32 v16, v16, v234
	v_mul_f32_e32 v17, v17, v235
	v_mul_f32_e32 v18, v18, v236
	v_mul_f32_e32 v19, v19, v237
	v_mul_f32_e32 v20, v28, v20
	v_mul_f32_e32 v21, v29, v21
	v_mul_f32_e32 v22, v30, v22
	v_mul_f32_e32 v23, v31, v23
	v_mul_f32_e32 v16, v24, v16
	v_mul_f32_e32 v17, v25, v17
	v_mul_f32_e32 v18, v26, v18
	v_mul_f32_e32 v19, v27, v19
	v_cvt_pk_bf16_f32 v28, v20, v21
	v_cvt_pk_bf16_f32 v29, v22, v23
	v_cvt_pk_bf16_f32 v30, v16, v17
	v_cvt_pk_bf16_f32 v31, v18, v19
	global_store_dwordx4 v238, v[28:31], s[40:41]
	s_waitcnt vmcnt(0)
; __device__ __forceinline__ u32x4v pack8(const f32x4& a, const f32x4& b) { u32x4v w; w.x = cvt_pk_bf16(a[0], a[1]); w.y = cvt_pk_bf16(a[2], a[3]); w.z = cvt_pk_bf16(b[0], b[1]); w.w = cvt_pk_bf16(b[2], b[3]); return w; }
; __device__ __forceinline__ float rstd_from_partials(const float* part, int row) {
;     const f32x4* p = (const f32x4*)(part + (size_t)row * 16); const f32x4 a = p[0], b = p[1], c = p[2], d = p[3];
;     const float s = ((a[0] + a[1]) + (a[2] + a[3])) + ((b[0] + b[1]) + (b[2] + b[3])) + ((c[0] + c[1]) + (c[2] + c[3])) + ((d[0] + d[1]) + (d[2] + d[3]));
;     return __builtin_amdgcn_rsqf(s * (1.0f / 1024.0f) + 1e-6f);
;     __device__ __forceinline__ void operator()(const f32x4 (&acc)[2][2][4][2], const Unit& u, int wr, int wc, int fr, int fq) const {
;     ...
;             for (int m = 0; m < 4; ++m) { const int r = row0 + ai * HALF + m * 16; const float rs = rstd_from_partials(part, r);
;                 f32x4 o[2];
; #pragma unroll
;                 for (int n = 0; n < 2; ++n) { const f32x4 g = acc[ai][0][m][n] * rs, up = acc[ai][1][m][n] * rs;
; #pragma unroll
;                     for (int e = 0; e < 4; ++e) o[n][e] = g[e] * __builtin_amdgcn_rcpf(1.0f + __builtin_amdgcn_exp2f(-1.44269504089f * g[e])) * up[e]; }
;                 *(u32x4v*)(H + (size_t)r * 2816 + hc0) = pack8(o[0], o[1]); }
	v_add_f32_e32 v230, v202, v203
	v_add_f32_e32 v231, v204, v205
	v_add_f32_e32 v232, v206, v207
	v_add_f32_e32 v233, v208, v209
	v_add_f32_e32 v234, v210, v211
	v_add_f32_e32 v235, v212, v213
	v_add_f32_e32 v236, v214, v215
	v_add_f32_e32 v237, v216, v217
	v_add_f32_e32 v230, v230, v231
	v_add_f32_e32 v232, v232, v233
	v_add_f32_e32 v234, v234, v235
	v_add_f32_e32 v236, v236, v237
	v_add_f32_e32 v230, v230, v232
	v_add_f32_e32 v230, v230, v234
	v_add_f32_e32 v230, v230, v236
	v_fmamk_f32 v230, v230, 0x3a800000, v152
	v_rsq_f32_e32 v229, v230
	v_add_u32_e32 v239, 0xf2000, v218
	v_mul_f32_e32 v4, v4, v229
	v_mul_f32_e32 v5, v5, v229
	v_mul_f32_e32 v6, v6, v229
	v_mul_f32_e32 v7, v7, v229
	v_mul_f32_e32 v0, v0, v229
	v_mul_f32_e32 v1, v1, v229
	v_mul_f32_e32 v2, v2, v229
	v_mul_f32_e32 v3, v3, v229
	v_mul_f32_e32 v12, v12, v229
	v_mul_f32_e32 v13, v13, v229
	v_mul_f32_e32 v14, v14, v229
	v_mul_f32_e32 v15, v15, v229
	v_mul_f32_e32 v8, v8, v229
	v_mul_f32_e32 v9, v9, v229
	v_mul_f32_e32 v10, v10, v229
	v_mul_f32_e32 v11, v11, v229
	v_mul_f32_e32 v230, 0xbfb8aa3b, v4
	v_mul_f32_e32 v231, 0xbfb8aa3b, v5
	v_mul_f32_e32 v232, 0xbfb8aa3b, v6
	v_mul_f32_e32 v233, 0xbfb8aa3b, v7
	v_mul_f32_e32 v234, 0xbfb8aa3b, v0
	v_mul_f32_e32 v235, 0xbfb8aa3b, v1
	v_mul_f32_e32 v236, 0xbfb8aa3b, v2
	v_mul_f32_e32 v237, 0xbfb8aa3b, v3
	v_exp_f32_e32 v230, v230
	v_exp_f32_e32 v231, v231
	v_exp_f32_e32 v232, v232
	v_exp_f32_e32 v233, v233
	v_exp_f32_e32 v234, v234
	v_exp_f32_e32 v235, v235
	v_exp_f32_e32 v236, v236
	v_exp_f32_e32 v237, v237
	v_add_f32_e32 v230, 1.0, v230
	v_add_f32_e32 v231, 1.0, v231
	v_add_f32_e32 v232, 1.0, v232
	v_add_f32_e32 v233, 1.0, v233
	v_add_f32_e32 v234, 1.0, v234
	v_add_f32_e32 v235, 1.0, v235
	v_add_f32_e32 v236, 1.0, v236
	v_add_f32_e32 v237, 1.0, v237
	v_rcp_f32_e32 v230, v230
	v_rcp_f32_e32 v231, v231
	v_rcp_f32_e32 v232, v232
	v_rcp_f32_e32 v233, v233
	v_rcp_f32_e32 v234, v234
	v_rcp_f32_e32 v235, v235
	v_rcp_f32_e32 v236, v236
	v_rcp_f32_e32 v237, v237
	v_mul_f32_e32 v4, v4, v230
	v_mul_f32_e32 v5, v5, v231
	v_mul_f32_e32 v6, v6, v232
	v_mul_f32_e32 v7, v7, v233
	v_mul_f32_e32 v0, v0, v234
	v_mul_f32_e32 v1, v1, v235
	v_mul_f32_e32 v2, v2, v236
	v_mul_f32_e32 v3, v3, v237
	v_mul_f32_e32 v4, v12, v4
	v_mul_f32_e32 v5, v13, v5
	v_mul_f32_e32 v6, v14, v6
	v_mul_f32_e32 v7, v15, v7
	v_mul_f32_e32 v0, v8, v0
	v_mul_f32_e32 v1, v9, v1
	v_mul_f32_e32 v2, v10, v2
	v_mul_f32_e32 v3, v11, v3
	v_cvt_pk_bf16_f32 v12, v4, v5
	v_cvt_pk_bf16_f32 v13, v6, v7
	v_cvt_pk_bf16_f32 v14, v0, v1
	v_cvt_pk_bf16_f32 v15, v2, v3
	global_store_dwordx4 v239, v[12:15], s[40:41]
	s_andn2_b64 vcc, exec, s[0:1]
	s_mov_b64 s[0:1], -1
	s_cbranch_vccnz .LBB0_571
	s_andn2_b64 vcc, exec, s[8:9]
	s_cbranch_vccnz .LBB0_570
	s_barrier
	s_branch .LBB0_570

; __device__ __forceinline__ u32x4v pack8(const f32x4& a, const f32x4& b) { u32x4v w; w.x = cvt_pk_bf16(a[0], a[1]); w.y = cvt_pk_bf16(a[2], a[3]); w.z = cvt_pk_bf16(b[0], b[1]); w.w = cvt_pk_bf16(b[2], b[3]); return w; }
; __device__ __forceinline__ float rstd_from_partials(const float* part, int row) {
;     const f32x4* p = (const f32x4*)(part + (size_t)row * 16); const f32x4 a = p[0], b = p[1], c = p[2], d = p[3];
;     const float s = ((a[0] + a[1]) + (a[2] + a[3])) + ((b[0] + b[1]) + (b[2] + b[3])) + ((c[0] + c[1]) + (c[2] + c[3])) + ((d[0] + d[1]) + (d[2] + d[3]));
;     return __builtin_amdgcn_rsqf(s * (1.0f / 1024.0f) + 1e-6f);
;     __device__ __forceinline__ void operator()(const f32x4 (&acc)[2][2][4][2], const Unit& u, int wr, int wc, int fr, int fq) const {
;     ...
;             for (int m = 0; m < 4; ++m) { const int r = row0 + ai * HALF + m * 16; const float rs = rstd_from_partials(part, r);
;                 f32x4 o[2];
; #pragma unroll
;                 for (int n = 0; n < 2; ++n) { const f32x4 g = acc[ai][0][m][n] * rs, up = acc[ai][1][m][n] * rs;
; #pragma unroll
;                     for (int e = 0; e < 4; ++e) o[n][e] = g[e] * __builtin_amdgcn_rcpf(1.0f + __builtin_amdgcn_exp2f(-1.44269504089f * g[e])) * up[e]; }
;                 *(u32x4v*)(H + (size_t)r * 2816 + hc0) = pack8(o[0], o[1]); }
.LBB0_1085:
	v_lshl_add_u32 v144, s22, 8, v146
	v_lshlrev_b32_e32 v145, 6, v144
	v_add_u32_e32 v153, 0x2000, v145
	global_load_dwordx4 v[154:157], v145, s[70:71] offset:0
	global_load_dwordx4 v[158:161], v145, s[70:71] offset:16
	global_load_dwordx4 v[162:165], v145, s[70:71] offset:32
	global_load_dwordx4 v[166:169], v145, s[70:71] offset:48
	global_load_dwordx4 v[170:173], v145, s[70:71] offset:1024
	global_load_dwordx4 v[174:177], v145, s[70:71] offset:1040
	global_load_dwordx4 v[178:181], v145, s[70:71] offset:1056
	global_load_dwordx4 v[182:185], v145, s[70:71] offset:1072
	global_load_dwordx4 v[186:189], v145, s[70:71] offset:2048
	global_load_dwordx4 v[190:193], v145, s[70:71] offset:2064
	global_load_dwordx4 v[194:197], v145, s[70:71] offset:2080
	global_load_dwordx4 v[198:201], v145, s[70:71] offset:2096
	global_load_dwordx4 v[202:205], v145, s[70:71] offset:3072
	global_load_dwordx4 v[206:209], v145, s[70:71] offset:3088
	global_load_dwordx4 v[210:213], v145, s[70:71] offset:3104
	global_load_dwordx4 v[214:217], v145, s[70:71] offset:3120
	v_mul_u32_u24_e32 v218, s49, v144
	v_lshl_or_b32 v219, s50, 7, v148
	v_lshl_add_u32 v218, v219, 1, v218
	s_waitcnt vmcnt(12)
	v_add_f32_e32 v230, v154, v155
	v_add_f32_e32 v231, v156, v157
	v_add_f32_e32 v232, v158, v159
	v_add_f32_e32 v233, v160, v161
	v_add_f32_e32 v234, v162, v163
	v_add_f32_e32 v235, v164, v165
	v_add_f32_e32 v236, v166, v167
	v_add_f32_e32 v237, v168, v169
	v_add_f32_e32 v230, v230, v231
	v_add_f32_e32 v232, v232, v233
	v_add_f32_e32 v234, v234, v235
	v_add_f32_e32 v236, v236, v237
	v_add_f32_e32 v230, v230, v232
	v_add_f32_e32 v230, v230, v234
	v_add_f32_e32 v230, v230, v236
	v_fmamk_f32 v230, v230, 0x3a800000, v152
	v_rsq_f32_e32 v222, v230
	global_load_dwordx4 v[154:157], v153, s[70:71] offset:0
	global_load_dwordx4 v[158:161], v153, s[70:71] offset:16
	global_load_dwordx4 v[162:165], v153, s[70:71] offset:32
	global_load_dwordx4 v[166:169], v153, s[70:71] offset:48
	v_mov_b32_e32 v238, v218
	v_mul_f32_e32 v116, v116, v222
	v_mul_f32_e32 v117, v117, v222
	v_mul_f32_e32 v118, v118, v222
	v_mul_f32_e32 v119, v119, v222
	v_mul_f32_e32 v112, v112, v222
	v_mul_f32_e32 v113, v113, v222
	v_mul_f32_e32 v114, v114, v222
	v_mul_f32_e32 v115, v115, v222
	v_mul_f32_e32 v124, v124, v222
	v_mul_f32_e32 v125, v125, v222
	v_mul_f32_e32 v126, v126, v222
	v_mul_f32_e32 v127, v127, v222
	v_mul_f32_e32 v120, v120, v222
	v_mul_f32_e32 v121, v121, v222
	v_mul_f32_e32 v122, v122, v222
	v_mul_f32_e32 v123, v123, v222
	v_mul_f32_e32 v230, 0xbfb8aa3b, v116
	v_mul_f32_e32 v231, 0xbfb8aa3b, v117
	v_mul_f32_e32 v232, 0xbfb8aa3b, v118
	v_mul_f32_e32 v233, 0xbfb8aa3b, v119
	v_mul_f32_e32 v234, 0xbfb8aa3b, v112
	v_mul_f32_e32 v235, 0xbfb8aa3b, v113
	v_mul_f32_e32 v236, 0xbfb8aa3b, v114
	v_mul_f32_e32 v237, 0xbfb8aa3b, v115
	v_exp_f32_e32 v230, v230
	v_exp_f32_e32 v231, v231
	v_exp_f32_e32 v232, v232
	v_exp_f32_e32 v233, v233
	v_exp_f32_e32 v234, v234
	v_exp_f32_e32 v235, v235
	v_exp_f32_e32 v236, v236
	v_exp_f32_e32 v237, v237
	v_add_f32_e32 v230, 1.0, v230
	v_add_f32_e32 v231, 1.0, v231
	v_add_f32_e32 v232, 1.0, v232
	v_add_f32_e32 v233, 1.0, v233
	v_add_f32_e32 v234, 1.0, v234
	v_add_f32_e32 v235, 1.0, v235
	v_add_f32_e32 v236, 1.0, v236
	v_add_f32_e32 v237, 1.0, v237
	v_rcp_f32_e32 v230, v230
	v_rcp_f32_e32 v231, v231
	v_rcp_f32_e32 v232, v232
	v_rcp_f32_e32 v233, v233
	v_rcp_f32_e32 v234, v234
	v_rcp_f32_e32 v235, v235
	v_rcp_f32_e32 v236, v236
	v_rcp_f32_e32 v237, v237
	v_mul_f32_e32 v116, v116, v230
	v_mul_f32_e32 v117, v117, v231
	v_mul_f32_e32 v118, v118, v232
	v_mul_f32_e32 v119, v119, v233
	v_mul_f32_e32 v112, v112, v234
	v_mul_f32_e32 v113, v113, v235
	v_mul_f32_e32 v114, v114, v236
	v_mul_f32_e32 v115, v115, v237
	v_mul_f32_e32 v116, v124, v116
	v_mul_f32_e32 v117, v125, v117
	v_mul_f32_e32 v118, v126, v118
	v_mul_f32_e32 v119, v127, v119
	v_mul_f32_e32 v112, v120, v112
	v_mul_f32_e32 v113, v121, v113
	v_mul_f32_e32 v114, v122, v114
	v_mul_f32_e32 v115, v123, v115
	v_cvt_pk_bf16_f32 v124, v116, v117
	v_cvt_pk_bf16_f32 v125, v118, v119
	v_cvt_pk_bf16_f32 v126, v112, v113
	v_cvt_pk_bf16_f32 v127, v114, v115
	global_store_dwordx4 v238, v[124:127], s[40:41]
	s_waitcnt vmcnt(12)
	v_add_f32_e32 v230, v170, v171
	v_add_f32_e32 v231, v172, v173
	v_add_f32_e32 v232, v174, v175
	v_add_f32_e32 v233, v176, v177
	v_add_f32_e32 v234, v178, v179
	v_add_f32_e32 v235, v180, v181
	v_add_f32_e32 v236, v182, v183
	v_add_f32_e32 v237, v184, v185
	v_add_f32_e32 v230, v230, v231
	v_add_f32_e32 v232, v232, v233
	v_add_f32_e32 v234, v234, v235
	v_add_f32_e32 v236, v236, v237
	v_add_f32_e32 v230, v230, v232
	v_add_f32_e32 v230, v230, v234
	v_add_f32_e32 v230, v230, v236
	v_fmamk_f32 v230, v230, 0x3a800000, v152
	v_rsq_f32_e32 v223, v230
	global_load_dwordx4 v[170:173], v153, s[70:71] offset:1024
	global_load_dwordx4 v[174:177], v153, s[70:71] offset:1040
	global_load_dwordx4 v[178:181], v153, s[70:71] offset:1056
	global_load_dwordx4 v[182:185], v153, s[70:71] offset:1072
	v_add_u32_e32 v239, 0x16000, v218
	v_mul_f32_e32 v100, v100, v223
	v_mul_f32_e32 v101, v101, v223
	v_mul_f32_e32 v102, v102, v223
	v_mul_f32_e32 v103, v103, v223
	v_mul_f32_e32 v96, v96, v223
	v_mul_f32_e32 v97, v97, v223
	v_mul_f32_e32 v98, v98, v223
	v_mul_f32_e32 v99, v99, v223
	v_mul_f32_e32 v108, v108, v223
	v_mul_f32_e32 v109, v109, v223
	v_mul_f32_e32 v110, v110, v223
	v_mul_f32_e32 v111, v111, v223
	v_mul_f32_e32 v104, v104, v223
	v_mul_f32_e32 v105, v105, v223
	v_mul_f32_e32 v106, v106, v223
	v_mul_f32_e32 v107, v107, v223
	v_mul_f32_e32 v230, 0xbfb8aa3b, v100
	v_mul_f32_e32 v231, 0xbfb8aa3b, v101
	v_mul_f32_e32 v232, 0xbfb8aa3b, v102
; __device__ __forceinline__ u32x4v pack8(const f32x4& a, const f32x4& b) { u32x4v w; w.x = cvt_pk_bf16(a[0], a[1]); w.y = cvt_pk_bf16(a[2], a[3]); w.z = cvt_pk_bf16(b[0], b[1]); w.w = cvt_pk_bf16(b[2], b[3]); return w; }
;     __device__ __forceinline__ void operator()(const f32x4 (&acc)[2][2][4][2], const Unit& u, int wr, int wc, int fr, int fq) const {
;     ...
;             for (int m = 0; m < 4; ++m) { const int r = row0 + ai * HALF + m * 16; const float rs = rstd_from_partials(part, r);
;                 f32x4 o[2];
; #pragma unroll
;                 for (int n = 0; n < 2; ++n) { const f32x4 g = acc[ai][0][m][n] * rs, up = acc[ai][1][m][n] * rs;
; #pragma unroll
;                     for (int e = 0; e < 4; ++e) o[n][e] = g[e] * __builtin_amdgcn_rcpf(1.0f + __builtin_amdgcn_exp2f(-1.44269504089f * g[e])) * up[e]; }
;                 *(u32x4v*)(H + (size_t)r * 2816 + hc0) = pack8(o[0], o[1]); }
	v_mul_f32_e32 v233, 0xbfb8aa3b, v103
	v_mul_f32_e32 v234, 0xbfb8aa3b, v96
	v_mul_f32_e32 v235, 0xbfb8aa3b, v97
	v_mul_f32_e32 v236, 0xbfb8aa3b, v98
	v_mul_f32_e32 v237, 0xbfb8aa3b, v99
	v_exp_f32_e32 v230, v230
	v_exp_f32_e32 v231, v231
	v_exp_f32_e32 v232, v232
	v_exp_f32_e32 v233, v233
	v_exp_f32_e32 v234, v234
	v_exp_f32_e32 v235, v235
	v_exp_f32_e32 v236, v236
	v_exp_f32_e32 v237, v237
	v_add_f32_e32 v230, 1.0, v230
	v_add_f32_e32 v231, 1.0, v231
	v_add_f32_e32 v232, 1.0, v232
	v_add_f32_e32 v233, 1.0, v233
	v_add_f32_e32 v234, 1.0, v234
	v_add_f32_e32 v235, 1.0, v235
	v_add_f32_e32 v236, 1.0, v236
	v_add_f32_e32 v237, 1.0, v237
	v_rcp_f32_e32 v230, v230
	v_rcp_f32_e32 v231, v231
	v_rcp_f32_e32 v232, v232
	v_rcp_f32_e32 v233, v233
	v_rcp_f32_e32 v234, v234
	v_rcp_f32_e32 v235, v235
	v_rcp_f32_e32 v236, v236
	v_rcp_f32_e32 v237, v237
	v_mul_f32_e32 v100, v100, v230
	v_mul_f32_e32 v101, v101, v231
	v_mul_f32_e32 v102, v102, v232
	v_mul_f32_e32 v103, v103, v233
	v_mul_f32_e32 v96, v96, v234
	v_mul_f32_e32 v97, v97, v235
	v_mul_f32_e32 v98, v98, v236
	v_mul_f32_e32 v99, v99, v237
	v_mul_f32_e32 v100, v108, v100
	v_mul_f32_e32 v101, v109, v101
	v_mul_f32_e32 v102, v110, v102
	v_mul_f32_e32 v103, v111, v103
	v_mul_f32_e32 v96, v104, v96
	v_mul_f32_e32 v97, v105, v97
	v_mul_f32_e32 v98, v106, v98
	v_mul_f32_e32 v99, v107, v99
	v_cvt_pk_bf16_f32 v108, v100, v101
	v_cvt_pk_bf16_f32 v109, v102, v103
	v_cvt_pk_bf16_f32 v110, v96, v97
	v_cvt_pk_bf16_f32 v111, v98, v99
	global_store_dwordx4 v239, v[108:111], s[40:41]
	s_waitcnt vmcnt(12)
	v_add_f32_e32 v230, v186, v187
	v_add_f32_e32 v231, v188, v189
	v_add_f32_e32 v232, v190, v191
	v_add_f32_e32 v233, v192, v193
	v_add_f32_e32 v234, v194, v195
	v_add_f32_e32 v235, v196, v197
	v_add_f32_e32 v236, v198, v199
	v_add_f32_e32 v237, v200, v201
	v_add_f32_e32 v230, v230, v231
	v_add_f32_e32 v232, v232, v233
	v_add_f32_e32 v234, v234, v235
	v_add_f32_e32 v236, v236, v237
	v_add_f32_e32 v230, v230, v232
	v_add_f32_e32 v230, v230, v234
	v_add_f32_e32 v230, v230, v236
	v_fmamk_f32 v230, v230, 0x3a800000, v152
	v_rsq_f32_e32 v224, v230
	global_load_dwordx4 v[186:189], v153, s[70:71] offset:2048
	global_load_dwordx4 v[190:193], v153, s[70:71] offset:2064
	global_load_dwordx4 v[194:197], v153, s[70:71] offset:2080
	global_load_dwordx4 v[198:201], v153, s[70:71] offset:2096
	v_add_u32_e32 v238, 0x2c000, v218
	v_mul_f32_e32 v84, v84, v224
	v_mul_f32_e32 v85, v85, v224
	v_mul_f32_e32 v86, v86, v224
	v_mul_f32_e32 v87, v87, v224
	v_mul_f32_e32 v80, v80, v224
	v_mul_f32_e32 v81, v81, v224
	v_mul_f32_e32 v82, v82, v224
	v_mul_f32_e32 v83, v83, v224
	v_mul_f32_e32 v92, v92, v224
	v_mul_f32_e32 v93, v93, v224
	v_mul_f32_e32 v94, v94, v224
	v_mul_f32_e32 v95, v95, v224
	v_mul_f32_e32 v88, v88, v224
	v_mul_f32_e32 v89, v89, v224
	v_mul_f32_e32 v90, v90, v224
	v_mul_f32_e32 v91, v91, v224
	v_mul_f32_e32 v230, 0xbfb8aa3b, v84
	v_mul_f32_e32 v231, 0xbfb8aa3b, v85
	v_mul_f32_e32 v232, 0xbfb8aa3b, v86
	v_mul_f32_e32 v233, 0xbfb8aa3b, v87
	v_mul_f32_e32 v234, 0xbfb8aa3b, v80
	v_mul_f32_e32 v235, 0xbfb8aa3b, v81
	v_mul_f32_e32 v236, 0xbfb8aa3b, v82
	v_mul_f32_e32 v237, 0xbfb8aa3b, v83
	v_exp_f32_e32 v230, v230
	v_exp_f32_e32 v231, v231
	v_exp_f32_e32 v232, v232
	v_exp_f32_e32 v233, v233
	v_exp_f32_e32 v234, v234
	v_exp_f32_e32 v235, v235
	v_exp_f32_e32 v236, v236
	v_exp_f32_e32 v237, v237
	v_add_f32_e32 v230, 1.0, v230
	v_add_f32_e32 v231, 1.0, v231
	v_add_f32_e32 v232, 1.0, v232
	v_add_f32_e32 v233, 1.0, v233
	v_add_f32_e32 v234, 1.0, v234
	v_add_f32_e32 v235, 1.0, v235
	v_add_f32_e32 v236, 1.0, v236
	v_add_f32_e32 v237, 1.0, v237
	v_rcp_f32_e32 v230, v230
	v_rcp_f32_e32 v231, v231
	v_rcp_f32_e32 v232, v232
	v_rcp_f32_e32 v233, v233
	v_rcp_f32_e32 v234, v234
	v_rcp_f32_e32 v235, v235
	v_rcp_f32_e32 v236, v236
	v_rcp_f32_e32 v237, v237
	v_mul_f32_e32 v84, v84, v230
	v_mul_f32_e32 v85, v85, v231
	v_mul_f32_e32 v86, v86, v232
	v_mul_f32_e32 v87, v87, v233
	v_mul_f32_e32 v80, v80, v234
	v_mul_f32_e32 v81, v81, v235
	v_mul_f32_e32 v82, v82, v236
	v_mul_f32_e32 v83, v83, v237
	v_mul_f32_e32 v84, v92, v84
	v_mul_f32_e32 v85, v93, v85
	v_mul_f32_e32 v86, v94, v86
	v_mul_f32_e32 v87, v95, v87
	v_mul_f32_e32 v80, v88, v80
	v_mul_f32_e32 v81, v89, v81
	v_mul_f32_e32 v82, v90, v82
	v_mul_f32_e32 v83, v91, v83
	v_cvt_pk_bf16_f32 v92, v84, v85
	v_cvt_pk_bf16_f32 v93, v86, v87
	v_cvt_pk_bf16_f32 v94, v80, v81
	v_cvt_pk_bf16_f32 v95, v82, v83
	global_store_dwordx4 v238, v[92:95], s[40:41]
	s_waitcnt vmcnt(12)
; __device__ __forceinline__ u32x4v pack8(const f32x4& a, const f32x4& b) { u32x4v w; w.x = cvt_pk_bf16(a[0], a[1]); w.y = cvt_pk_bf16(a[2], a[3]); w.z = cvt_pk_bf16(b[0], b[1]); w.w = cvt_pk_bf16(b[2], b[3]); return w; }
; __device__ __forceinline__ float rstd_from_partials(const float* part, int row) {
;     const f32x4* p = (const f32x4*)(part + (size_t)row * 16); const f32x4 a = p[0], b = p[1], c = p[2], d = p[3];
;     const float s = ((a[0] + a[1]) + (a[2] + a[3])) + ((b[0] + b[1]) + (b[2] + b[3])) + ((c[0] + c[1]) + (c[2] + c[3])) + ((d[0] + d[1]) + (d[2] + d[3]));
;     return __builtin_amdgcn_rsqf(s * (1.0f / 1024.0f) + 1e-6f);
;     __device__ __forceinline__ void operator()(const f32x4 (&acc)[2][2][4][2], const Unit& u, int wr, int wc, int fr, int fq) const {
;     ...
;             for (int m = 0; m < 4; ++m) { const int r = row0 + ai * HALF + m * 16; const float rs = rstd_from_partials(part, r);
;                 f32x4 o[2];
; #pragma unroll
;                 for (int n = 0; n < 2; ++n) { const f32x4 g = acc[ai][0][m][n] * rs, up = acc[ai][1][m][n] * rs;
; #pragma unroll
;                     for (int e = 0; e < 4; ++e) o[n][e] = g[e] * __builtin_amdgcn_rcpf(1.0f + __builtin_amdgcn_exp2f(-1.44269504089f * g[e])) * up[e]; }
;                 *(u32x4v*)(H + (size_t)r * 2816 + hc0) = pack8(o[0], o[1]); }
	v_add_f32_e32 v230, v202, v203
	v_add_f32_e32 v231, v204, v205
	v_add_f32_e32 v232, v206, v207
	v_add_f32_e32 v233, v208, v209
	v_add_f32_e32 v234, v210, v211
	v_add_f32_e32 v235, v212, v213
	v_add_f32_e32 v236, v214, v215
	v_add_f32_e32 v237, v216, v217
	v_add_f32_e32 v230, v230, v231
	v_add_f32_e32 v232, v232, v233
	v_add_f32_e32 v234, v234, v235
	v_add_f32_e32 v236, v236, v237
	v_add_f32_e32 v230, v230, v232
	v_add_f32_e32 v230, v230, v234
	v_add_f32_e32 v230, v230, v236
	v_fmamk_f32 v230, v230, 0x3a800000, v152
	v_rsq_f32_e32 v225, v230
	global_load_dwordx4 v[202:205], v153, s[70:71] offset:3072
	global_load_dwordx4 v[206:209], v153, s[70:71] offset:3088
	global_load_dwordx4 v[210:213], v153, s[70:71] offset:3104
	global_load_dwordx4 v[214:217], v153, s[70:71] offset:3120
	v_add_u32_e32 v239, 0x42000, v218
	v_mul_f32_e32 v68, v68, v225
	v_mul_f32_e32 v69, v69, v225
	v_mul_f32_e32 v70, v70, v225
	v_mul_f32_e32 v71, v71, v225
	v_mul_f32_e32 v64, v64, v225
	v_mul_f32_e32 v65, v65, v225
	v_mul_f32_e32 v66, v66, v225
	v_mul_f32_e32 v67, v67, v225
	v_mul_f32_e32 v76, v76, v225
	v_mul_f32_e32 v77, v77, v225
	v_mul_f32_e32 v78, v78, v225
	v_mul_f32_e32 v79, v79, v225
	v_mul_f32_e32 v72, v72, v225
	v_mul_f32_e32 v73, v73, v225
	v_mul_f32_e32 v74, v74, v225
	v_mul_f32_e32 v75, v75, v225
	v_mul_f32_e32 v230, 0xbfb8aa3b, v68
	v_mul_f32_e32 v231, 0xbfb8aa3b, v69
	v_mul_f32_e32 v232, 0xbfb8aa3b, v70
	v_mul_f32_e32 v233, 0xbfb8aa3b, v71
	v_mul_f32_e32 v234, 0xbfb8aa3b, v64
	v_mul_f32_e32 v235, 0xbfb8aa3b, v65
	v_mul_f32_e32 v236, 0xbfb8aa3b, v66
	v_mul_f32_e32 v237, 0xbfb8aa3b, v67
	v_exp_f32_e32 v230, v230
	v_exp_f32_e32 v231, v231
	v_exp_f32_e32 v232, v232
	v_exp_f32_e32 v233, v233
	v_exp_f32_e32 v234, v234
	v_exp_f32_e32 v235, v235
	v_exp_f32_e32 v236, v236
	v_exp_f32_e32 v237, v237
	v_add_f32_e32 v230, 1.0, v230
	v_add_f32_e32 v231, 1.0, v231
	v_add_f32_e32 v232, 1.0, v232
	v_add_f32_e32 v233, 1.0, v233
	v_add_f32_e32 v234, 1.0, v234
	v_add_f32_e32 v235, 1.0, v235
	v_add_f32_e32 v236, 1.0, v236
	v_add_f32_e32 v237, 1.0, v237
	v_rcp_f32_e32 v230, v230
	v_rcp_f32_e32 v231, v231
	v_rcp_f32_e32 v232, v232
	v_rcp_f32_e32 v233, v233
	v_rcp_f32_e32 v234, v234
	v_rcp_f32_e32 v235, v235
	v_rcp_f32_e32 v236, v236
	v_rcp_f32_e32 v237, v237
	v_mul_f32_e32 v68, v68, v230
	v_mul_f32_e32 v69, v69, v231
	v_mul_f32_e32 v70, v70, v232
	v_mul_f32_e32 v71, v71, v233
	v_mul_f32_e32 v64, v64, v234
	v_mul_f32_e32 v65, v65, v235
	v_mul_f32_e32 v66, v66, v236
	v_mul_f32_e32 v67, v67, v237
	v_mul_f32_e32 v68, v76, v68
	v_mul_f32_e32 v69, v77, v69
	v_mul_f32_e32 v70, v78, v70
	v_mul_f32_e32 v71, v79, v71
	v_mul_f32_e32 v64, v72, v64
	v_mul_f32_e32 v65, v73, v65
	v_mul_f32_e32 v66, v74, v66
	v_mul_f32_e32 v67, v75, v67
	v_cvt_pk_bf16_f32 v76, v68, v69
	v_cvt_pk_bf16_f32 v77, v70, v71
	v_cvt_pk_bf16_f32 v78, v64, v65
	v_cvt_pk_bf16_f32 v79, v66, v67
	global_store_dwordx4 v239, v[76:79], s[40:41]
	s_waitcnt vmcnt(12)
	v_add_f32_e32 v230, v154, v155
	v_add_f32_e32 v231, v156, v157
	v_add_f32_e32 v232, v158, v159
	v_add_f32_e32 v233, v160, v161
	v_add_f32_e32 v234, v162, v163
	v_add_f32_e32 v235, v164, v165
	v_add_f32_e32 v236, v166, v167
	v_add_f32_e32 v237, v168, v169
	v_add_f32_e32 v230, v230, v231
	v_add_f32_e32 v232, v232, v233
	v_add_f32_e32 v234, v234, v235
	v_add_f32_e32 v236, v236, v237
	v_add_f32_e32 v230, v230, v232
	v_add_f32_e32 v230, v230, v234
	v_add_f32_e32 v230, v230, v236
	v_fmamk_f32 v230, v230, 0x3a800000, v152
	v_rsq_f32_e32 v226, v230
	v_add_u32_e32 v238, 0xb0000, v218
	v_mul_f32_e32 v52, v52, v226
	v_mul_f32_e32 v53, v53, v226
	v_mul_f32_e32 v54, v54, v226
	v_mul_f32_e32 v55, v55, v226
	v_mul_f32_e32 v48, v48, v226
	v_mul_f32_e32 v49, v49, v226
	v_mul_f32_e32 v50, v50, v226
	v_mul_f32_e32 v51, v51, v226
	v_mul_f32_e32 v60, v60, v226
	v_mul_f32_e32 v61, v61, v226
	v_mul_f32_e32 v62, v62, v226
	v_mul_f32_e32 v63, v63, v226
	v_mul_f32_e32 v56, v56, v226
	v_mul_f32_e32 v57, v57, v226
	v_mul_f32_e32 v58, v58, v226
	v_mul_f32_e32 v59, v59, v226
	v_mul_f32_e32 v230, 0xbfb8aa3b, v52
	v_mul_f32_e32 v231, 0xbfb8aa3b, v53
	v_mul_f32_e32 v232, 0xbfb8aa3b, v54
	v_mul_f32_e32 v233, 0xbfb8aa3b, v55
	v_mul_f32_e32 v234, 0xbfb8aa3b, v48
	v_mul_f32_e32 v235, 0xbfb8aa3b, v49
	v_mul_f32_e32 v236, 0xbfb8aa3b, v50
	v_mul_f32_e32 v237, 0xbfb8aa3b, v51
	v_exp_f32_e32 v230, v230
	v_exp_f32_e32 v231, v231
	v_exp_f32_e32 v232, v232
	v_exp_f32_e32 v233, v233
	v_exp_f32_e32 v234, v234
	v_exp_f32_e32 v235, v235
	v_exp_f32_e32 v236, v236
	v_exp_f32_e32 v237, v237
	v_add_f32_e32 v230, 1.0, v230
	v_add_f32_e32 v231, 1.0, v231
	v_add_f32_e32 v232, 1.0, v232
	v_add_f32_e32 v233, 1.0, v233
	v_add_f32_e32 v234, 1.0, v234
	v_add_f32_e32 v235, 1.0, v235
	v_add_f32_e32 v236, 1.0, v236
	v_add_f32_e32 v237, 1.0, v237
	v_rcp_f32_e32 v230, v230
	v_rcp_f32_e32 v231, v231
	v_rcp_f32_e32 v232, v232
	v_rcp_f32_e32 v233, v233
	v_rcp_f32_e32 v234, v234
	v_rcp_f32_e32 v235, v235
	v_rcp_f32_e32 v236, v236
	v_rcp_f32_e32 v237, v237
	v_mul_f32_e32 v52, v52, v230
	v_mul_f32_e32 v53, v53, v231
	v_mul_f32_e32 v54, v54, v232
	v_mul_f32_e32 v55, v55, v233
	v_mul_f32_e32 v48, v48, v234
	v_mul_f32_e32 v49, v49, v235
	v_mul_f32_e32 v50, v50, v236
	v_mul_f32_e32 v51, v51, v237
	v_mul_f32_e32 v52, v60, v52
	v_mul_f32_e32 v53, v61, v53
	v_mul_f32_e32 v54, v62, v54
	v_mul_f32_e32 v55, v63, v55
	v_mul_f32_e32 v48, v56, v48
	v_mul_f32_e32 v49, v57, v49
	v_mul_f32_e32 v50, v58, v50
	v_mul_f32_e32 v51, v59, v51
	v_cvt_pk_bf16_f32 v60, v52, v53
	v_cvt_pk_bf16_f32 v61, v54, v55
	v_cvt_pk_bf16_f32 v62, v48, v49
	v_cvt_pk_bf16_f32 v63, v50, v51
	global_store_dwordx4 v238, v[60:63], s[40:41]
	s_waitcnt vmcnt(8)
; __device__ __forceinline__ u32x4v pack8(const f32x4& a, const f32x4& b) { u32x4v w; w.x = cvt_pk_bf16(a[0], a[1]); w.y = cvt_pk_bf16(a[2], a[3]); w.z = cvt_pk_bf16(b[0], b[1]); w.w = cvt_pk_bf16(b[2], b[3]); return w; }
; __device__ __forceinline__ float rstd_from_partials(const float* part, int row) {
;     const f32x4* p = (const f32x4*)(part + (size_t)row * 16); const f32x4 a = p[0], b = p[1], c = p[2], d = p[3];
;     const float s = ((a[0] + a[1]) + (a[2] + a[3])) + ((b[0] + b[1]) + (b[2] + b[3])) + ((c[0] + c[1]) + (c[2] + c[3])) + ((d[0] + d[1]) + (d[2] + d[3]));
;     return __builtin_amdgcn_rsqf(s * (1.0f / 1024.0f) + 1e-6f);
;     __device__ __forceinline__ void operator()(const f32x4 (&acc)[2][2][4][2], const Unit& u, int wr, int wc, int fr, int fq) const {
;     ...
;             for (int m = 0; m < 4; ++m) { const int r = row0 + ai * HALF + m * 16; const float rs = rstd_from_partials(part, r);
;                 f32x4 o[2];
; #pragma unroll
;                 for (int n = 0; n < 2; ++n) { const f32x4 g = acc[ai][0][m][n] * rs, up = acc[ai][1][m][n] * rs;
; #pragma unroll
;                     for (int e = 0; e < 4; ++e) o[n][e] = g[e] * __builtin_amdgcn_rcpf(1.0f + __builtin_amdgcn_exp2f(-1.44269504089f * g[e])) * up[e]; }
;                 *(u32x4v*)(H + (size_t)r * 2816 + hc0) = pack8(o[0], o[1]); }
	v_add_f32_e32 v230, v170, v171
	v_add_f32_e32 v231, v172, v173
	v_add_f32_e32 v232, v174, v175
	v_add_f32_e32 v233, v176, v177
	v_add_f32_e32 v234, v178, v179
	v_add_f32_e32 v235, v180, v181
	v_add_f32_e32 v236, v182, v183
	v_add_f32_e32 v237, v184, v185
	v_add_f32_e32 v230, v230, v231
	v_add_f32_e32 v232, v232, v233
	v_add_f32_e32 v234, v234, v235
	v_add_f32_e32 v236, v236, v237
	v_add_f32_e32 v230, v230, v232
	v_add_f32_e32 v230, v230, v234
	v_add_f32_e32 v230, v230, v236
	v_fmamk_f32 v230, v230, 0x3a800000, v152
	v_rsq_f32_e32 v227, v230
	v_add_u32_e32 v239, 0xc6000, v218
	v_mul_f32_e32 v36, v36, v227
	v_mul_f32_e32 v37, v37, v227
	v_mul_f32_e32 v38, v38, v227
	v_mul_f32_e32 v39, v39, v227
	v_mul_f32_e32 v32, v32, v227
	v_mul_f32_e32 v33, v33, v227
	v_mul_f32_e32 v34, v34, v227
	v_mul_f32_e32 v35, v35, v227
	v_mul_f32_e32 v44, v44, v227
	v_mul_f32_e32 v45, v45, v227
	v_mul_f32_e32 v46, v46, v227
	v_mul_f32_e32 v47, v47, v227
	v_mul_f32_e32 v40, v40, v227
	v_mul_f32_e32 v41, v41, v227
	v_mul_f32_e32 v42, v42, v227
	v_mul_f32_e32 v43, v43, v227
	v_mul_f32_e32 v230, 0xbfb8aa3b, v36
	v_mul_f32_e32 v231, 0xbfb8aa3b, v37
	v_mul_f32_e32 v232, 0xbfb8aa3b, v38
	v_mul_f32_e32 v233, 0xbfb8aa3b, v39
	v_mul_f32_e32 v234, 0xbfb8aa3b, v32
	v_mul_f32_e32 v235, 0xbfb8aa3b, v33
	v_mul_f32_e32 v236, 0xbfb8aa3b, v34
	v_mul_f32_e32 v237, 0xbfb8aa3b, v35
	v_exp_f32_e32 v230, v230
	v_exp_f32_e32 v231, v231
	v_exp_f32_e32 v232, v232
	v_exp_f32_e32 v233, v233
	v_exp_f32_e32 v234, v234
	v_exp_f32_e32 v235, v235
	v_exp_f32_e32 v236, v236
	v_exp_f32_e32 v237, v237
	v_add_f32_e32 v230, 1.0, v230
	v_add_f32_e32 v231, 1.0, v231
	v_add_f32_e32 v232, 1.0, v232
	v_add_f32_e32 v233, 1.0, v233
	v_add_f32_e32 v234, 1.0, v234
	v_add_f32_e32 v235, 1.0, v235
	v_add_f32_e32 v236, 1.0, v236
	v_add_f32_e32 v237, 1.0, v237
	v_rcp_f32_e32 v230, v230
	v_rcp_f32_e32 v231, v231
	v_rcp_f32_e32 v232, v232
	v_rcp_f32_e32 v233, v233
	v_rcp_f32_e32 v234, v234
	v_rcp_f32_e32 v235, v235
	v_rcp_f32_e32 v236, v236
	v_rcp_f32_e32 v237, v237
	v_mul_f32_e32 v36, v36, v230
	v_mul_f32_e32 v37, v37, v231
	v_mul_f32_e32 v38, v38, v232
	v_mul_f32_e32 v39, v39, v233
	v_mul_f32_e32 v32, v32, v234
	v_mul_f32_e32 v33, v33, v235
	v_mul_f32_e32 v34, v34, v236
	v_mul_f32_e32 v35, v35, v237
	v_mul_f32_e32 v36, v44, v36
	v_mul_f32_e32 v37, v45, v37
	v_mul_f32_e32 v38, v46, v38
	v_mul_f32_e32 v39, v47, v39
	v_mul_f32_e32 v32, v40, v32
	v_mul_f32_e32 v33, v41, v33
	v_mul_f32_e32 v34, v42, v34
	v_mul_f32_e32 v35, v43, v35
	v_cvt_pk_bf16_f32 v44, v36, v37
	v_cvt_pk_bf16_f32 v45, v38, v39
	v_cvt_pk_bf16_f32 v46, v32, v33
	v_cvt_pk_bf16_f32 v47, v34, v35
	global_store_dwordx4 v239, v[44:47], s[40:41]
	s_waitcnt vmcnt(4)
	v_add_f32_e32 v230, v186, v187
	v_add_f32_e32 v231, v188, v189
	v_add_f32_e32 v232, v190, v191
	v_add_f32_e32 v233, v192, v193
	v_add_f32_e32 v234, v194, v195
	v_add_f32_e32 v235, v196, v197
	v_add_f32_e32 v236, v198, v199
	v_add_f32_e32 v237, v200, v201
	v_add_f32_e32 v230, v230, v231
	v_add_f32_e32 v232, v232, v233
	v_add_f32_e32 v234, v234, v235
	v_add_f32_e32 v236, v236, v237
	v_add_f32_e32 v230, v230, v232
	v_add_f32_e32 v230, v230, v234
	v_add_f32_e32 v230, v230, v236
	v_fmamk_f32 v230, v230, 0x3a800000, v152
	v_rsq_f32_e32 v228, v230
	v_add_u32_e32 v238, 0xdc000, v218
	v_mul_f32_e32 v20, v20, v228
	v_mul_f32_e32 v21, v21, v228
	v_mul_f32_e32 v22, v22, v228
	v_mul_f32_e32 v23, v23, v228
	v_mul_f32_e32 v16, v16, v228
	v_mul_f32_e32 v17, v17, v228
	v_mul_f32_e32 v18, v18, v228
	v_mul_f32_e32 v19, v19, v228
	v_mul_f32_e32 v28, v28, v228
	v_mul_f32_e32 v29, v29, v228
	v_mul_f32_e32 v30, v30, v228
	v_mul_f32_e32 v31, v31, v228
	v_mul_f32_e32 v24, v24, v228
	v_mul_f32_e32 v25, v25, v228
	v_mul_f32_e32 v26, v26, v228
	v_mul_f32_e32 v27, v27, v228
	v_mul_f32_e32 v230, 0xbfb8aa3b, v20
	v_mul_f32_e32 v231, 0xbfb8aa3b, v21
	v_mul_f32_e32 v232, 0xbfb8aa3b, v22
	v_mul_f32_e32 v233, 0xbfb8aa3b, v23
	v_mul_f32_e32 v234, 0xbfb8aa3b, v16
	v_mul_f32_e32 v235, 0xbfb8aa3b, v17
	v_mul_f32_e32 v236, 0xbfb8aa3b, v18
	v_mul_f32_e32 v237, 0xbfb8aa3b, v19
	v_exp_f32_e32 v230, v230
	v_exp_f32_e32 v231, v231
	v_exp_f32_e32 v232, v232
	v_exp_f32_e32 v233, v233
	v_exp_f32_e32 v234, v234
	v_exp_f32_e32 v235, v235
	v_exp_f32_e32 v236, v236
	v_exp_f32_e32 v237, v237
	v_add_f32_e32 v230, 1.0, v230
	v_add_f32_e32 v231, 1.0, v231
	v_add_f32_e32 v232, 1.0, v232
	v_add_f32_e32 v233, 1.0, v233
	v_add_f32_e32 v234, 1.0, v234
	v_add_f32_e32 v235, 1.0, v235
	v_add_f32_e32 v236, 1.0, v236
	v_add_f32_e32 v237, 1.0, v237
	v_rcp_f32_e32 v230, v230
	v_rcp_f32_e32 v231, v231
	v_rcp_f32_e32 v232, v232
	v_rcp_f32_e32 v233, v233
	v_rcp_f32_e32 v234, v234
	v_rcp_f32_e32 v235, v235
	v_rcp_f32_e32 v236, v236
	v_rcp_f32_e32 v237, v237
	v_mul_f32_e32 v20, v20, v230
	v_mul_f32_e32 v21, v21, v231
	v_mul_f32_e32 v22, v22, v232
	v_mul_f32_e32 v23, v23, v233
	v_mul_f32_e32 v16, v16, v234
	v_mul_f32_e32 v17, v17, v235
	v_mul_f32_e32 v18, v18, v236
	v_mul_f32_e32 v19, v19, v237
	v_mul_f32_e32 v20, v28, v20
	v_mul_f32_e32 v21, v29, v21
	v_mul_f32_e32 v22, v30, v22
	v_mul_f32_e32 v23, v31, v23
	v_mul_f32_e32 v16, v24, v16
	v_mul_f32_e32 v17, v25, v17
	v_mul_f32_e32 v18, v26, v18
	v_mul_f32_e32 v19, v27, v19
	v_cvt_pk_bf16_f32 v28, v20, v21
	v_cvt_pk_bf16_f32 v29, v22, v23
	v_cvt_pk_bf16_f32 v30, v16, v17
	v_cvt_pk_bf16_f32 v31, v18, v19
	global_store_dwordx4 v238, v[28:31], s[40:41]
	s_waitcnt vmcnt(0)
; __device__ __forceinline__ u32x4v pack8(const f32x4& a, const f32x4& b) { u32x4v w; w.x = cvt_pk_bf16(a[0], a[1]); w.y = cvt_pk_bf16(a[2], a[3]); w.z = cvt_pk_bf16(b[0], b[1]); w.w = cvt_pk_bf16(b[2], b[3]); return w; }
; __device__ __forceinline__ float rstd_from_partials(const float* part, int row) {
;     const f32x4* p = (const f32x4*)(part + (size_t)row * 16); const f32x4 a = p[0], b = p[1], c = p[2], d = p[3];
;     const float s = ((a[0] + a[1]) + (a[2] + a[3])) + ((b[0] + b[1]) + (b[2] + b[3])) + ((c[0] + c[1]) + (c[2] + c[3])) + ((d[0] + d[1]) + (d[2] + d[3]));
;     return __builtin_amdgcn_rsqf(s * (1.0f / 1024.0f) + 1e-6f);
;     __device__ __forceinline__ void operator()(const f32x4 (&acc)[2][2][4][2], const Unit& u, int wr, int wc, int fr, int fq) const {
;     ...
;             for (int m = 0; m < 4; ++m) { const int r = row0 + ai * HALF + m * 16; const float rs = rstd_from_partials(part, r);
;                 f32x4 o[2];
; #pragma unroll
;                 for (int n = 0; n < 2; ++n) { const f32x4 g = acc[ai][0][m][n] * rs, up = acc[ai][1][m][n] * rs;
; #pragma unroll
;                     for (int e = 0; e < 4; ++e) o[n][e] = g[e] * __builtin_amdgcn_rcpf(1.0f + __builtin_amdgcn_exp2f(-1.44269504089f * g[e])) * up[e]; }
;                 *(u32x4v*)(H + (size_t)r * 2816 + hc0) = pack8(o[0], o[1]); }
	v_add_f32_e32 v230, v202, v203
	v_add_f32_e32 v231, v204, v205
	v_add_f32_e32 v232, v206, v207
	v_add_f32_e32 v233, v208, v209
	v_add_f32_e32 v234, v210, v211
	v_add_f32_e32 v235, v212, v213
	v_add_f32_e32 v236, v214, v215
	v_add_f32_e32 v237, v216, v217
	v_add_f32_e32 v230, v230, v231
	v_add_f32_e32 v232, v232, v233
	v_add_f32_e32 v234, v234, v235
	v_add_f32_e32 v236, v236, v237
	v_add_f32_e32 v230, v230, v232
	v_add_f32_e32 v230, v230, v234
	v_add_f32_e32 v230, v230, v236
	v_fmamk_f32 v230, v230, 0x3a800000, v152
	v_rsq_f32_e32 v229, v230
	v_add_u32_e32 v239, 0xf2000, v218
	v_mul_f32_e32 v4, v4, v229
	v_mul_f32_e32 v5, v5, v229
	v_mul_f32_e32 v6, v6, v229
	v_mul_f32_e32 v7, v7, v229
	v_mul_f32_e32 v0, v0, v229
	v_mul_f32_e32 v1, v1, v229
	v_mul_f32_e32 v2, v2, v229
	v_mul_f32_e32 v3, v3, v229
	v_mul_f32_e32 v12, v12, v229
	v_mul_f32_e32 v13, v13, v229
	v_mul_f32_e32 v14, v14, v229
	v_mul_f32_e32 v15, v15, v229
	v_mul_f32_e32 v8, v8, v229
	v_mul_f32_e32 v9, v9, v229
	v_mul_f32_e32 v10, v10, v229
	v_mul_f32_e32 v11, v11, v229
	v_mul_f32_e32 v230, 0xbfb8aa3b, v4
	v_mul_f32_e32 v231, 0xbfb8aa3b, v5
	v_mul_f32_e32 v232, 0xbfb8aa3b, v6
	v_mul_f32_e32 v233, 0xbfb8aa3b, v7
	v_mul_f32_e32 v234, 0xbfb8aa3b, v0
	v_mul_f32_e32 v235, 0xbfb8aa3b, v1
	v_mul_f32_e32 v236, 0xbfb8aa3b, v2
	v_mul_f32_e32 v237, 0xbfb8aa3b, v3
	v_exp_f32_e32 v230, v230
	v_exp_f32_e32 v231, v231
	v_exp_f32_e32 v232, v232
	v_exp_f32_e32 v233, v233
	v_exp_f32_e32 v234, v234
	v_exp_f32_e32 v235, v235
	v_exp_f32_e32 v236, v236
	v_exp_f32_e32 v237, v237
	v_add_f32_e32 v230, 1.0, v230
	v_add_f32_e32 v231, 1.0, v231
	v_add_f32_e32 v232, 1.0, v232
	v_add_f32_e32 v233, 1.0, v233
	v_add_f32_e32 v234, 1.0, v234
	v_add_f32_e32 v235, 1.0, v235
	v_add_f32_e32 v236, 1.0, v236
	v_add_f32_e32 v237, 1.0, v237
	v_rcp_f32_e32 v230, v230
	v_rcp_f32_e32 v231, v231
	v_rcp_f32_e32 v232, v232
	v_rcp_f32_e32 v233, v233
	v_rcp_f32_e32 v234, v234
	v_rcp_f32_e32 v235, v235
	v_rcp_f32_e32 v236, v236
	v_rcp_f32_e32 v237, v237
	v_mul_f32_e32 v4, v4, v230
	v_mul_f32_e32 v5, v5, v231
	v_mul_f32_e32 v6, v6, v232
	v_mul_f32_e32 v7, v7, v233
	v_mul_f32_e32 v0, v0, v234
	v_mul_f32_e32 v1, v1, v235
	v_mul_f32_e32 v2, v2, v236
	v_mul_f32_e32 v3, v3, v237
	v_mul_f32_e32 v4, v12, v4
	v_mul_f32_e32 v5, v13, v5
	v_mul_f32_e32 v6, v14, v6
	v_mul_f32_e32 v7, v15, v7
	v_mul_f32_e32 v0, v8, v0
	v_mul_f32_e32 v1, v9, v1
	v_mul_f32_e32 v2, v10, v2
	v_mul_f32_e32 v3, v11, v3
	v_cvt_pk_bf16_f32 v12, v4, v5
	v_cvt_pk_bf16_f32 v13, v6, v7
	v_cvt_pk_bf16_f32 v14, v0, v1
	v_cvt_pk_bf16_f32 v15, v2, v3
	global_store_dwordx4 v239, v[12:15], s[40:41]
	s_andn2_b64 vcc, exec, s[0:1]
	s_mov_b64 s[0:1], -1
	s_cbranch_vccnz .LBB0_1078
	s_andn2_b64 vcc, exec, s[8:9]
	s_cbranch_vccnz .LBB0_1077
	s_barrier
	s_branch .LBB0_1077
